# E21: PLE epilogue y2/pp row loads issued one half-batch earlier (saddr form, renamed into dead regs, vmcnt waits regenerated) on top of v7
# speedup vs baseline: 1.0031x; 1.0021x over previous
.LBB0_1373:
	v_ashrrev_i32_e32 v225, 31, v224
	v_lshlrev_b64 v[108:109], 2, v[224:225]
	v_readlane_b32 s4, v254, 7
	v_lshl_add_u64 v[226:227], s[20:21], 0, v[108:109]
	v_lshl_add_u64 v[228:229], s[22:23], 0, v[108:109]
	v_lshl_add_u64 v[230:231], s[24:25], 0, v[108:109]
	v_lshl_add_u64 v[132:133], s[26:27], 0, v[108:109]
	v_lshl_add_u32 v205, v104, 3, s4
	global_load_dwordx4 v[112:115], v[226:227], off offset:16
	global_load_dwordx4 v[128:131], v[226:227], off
	global_load_dwordx4 v[124:127], v[228:229], off offset:16
	global_load_dwordx4 v[136:139], v[228:229], off
	global_load_dwordx4 v[104:107], v[230:231], off offset:16
	global_load_dwordx4 v[116:119], v[230:231], off
	global_load_dwordx4 v[108:111], v[132:133], off offset:16
	s_nop 0
	global_load_dwordx4 v[132:135], v[132:133], off
	v_add_co_u32_e32 v160, vcc, s8, v222
	ds_read_b64 v[206:207], v205
	s_nop 0
	v_addc_co_u32_e32 v161, vcc, 0, v223, vcc
	global_load_dwordx4 v[168:171], v[160:161], off
	v_add_co_u32_e32 v160, vcc, s8, v220
	s_waitcnt lgkmcnt(0)
	v_mul_f32_e64 v210, v207, -v206
	v_addc_co_u32_e32 v161, vcc, 0, v221, vcc
	global_load_dwordx4 v[172:175], v[160:161], off
	v_add_co_u32_e32 v160, vcc, s9, v222
	s_nop 0
	v_addc_co_u32_e32 v161, vcc, 0, v223, vcc
	v_add_co_u32_e32 v164, vcc, s9, v220
	global_load_dwordx4 v[160:163], v[160:161], off
	s_nop 0
	v_addc_co_u32_e32 v165, vcc, 0, v221, vcc
	global_load_dwordx4 v[164:167], v[164:165], off
	s_add_u32 s98, s16, 0x80000
	s_addc_u32 s99, s17, 0
	global_load_dwordx4 v[250:253], v200, s[98:99]
	s_add_u32 s98, s28, 0x80000
	s_addc_u32 s99, s29, 0
	global_load_dwordx4 v[246:249], v200, s[98:99]
	s_waitcnt vmcnt(17)
	v_lshlrev_b32_e32 v208, 16, v184
	v_and_b32_e32 v209, 0xffff0000, v184
	v_lshlrev_b32_e32 v184, 16, v185
	v_and_b32_e32 v185, 0xffff0000, v185
	v_lshlrev_b32_e32 v212, 16, v186
	v_and_b32_e32 v213, 0xffff0000, v186
	v_lshlrev_b32_e32 v186, 16, v187
	v_and_b32_e32 v187, 0xffff0000, v187
	v_pk_fma_f32 v[208:209], v[206:207], v[208:209], v[210:211] op_sel:[1,0,0] op_sel_hi:[1,1,0]
	v_pk_fma_f32 v[184:185], v[206:207], v[184:185], v[210:211] op_sel:[1,0,0] op_sel_hi:[1,1,0]
	v_pk_fma_f32 v[212:213], v[206:207], v[212:213], v[210:211] op_sel:[1,0,0] op_sel_hi:[1,1,0]
	v_pk_fma_f32 v[186:187], v[206:207], v[186:187], v[210:211] op_sel:[1,0,0] op_sel_hi:[1,1,0]
	s_waitcnt vmcnt(15)
	v_lshlrev_b32_e32 v232, 16, v188
	v_and_b32_e32 v233, 0xffff0000, v188
	v_lshlrev_b32_e32 v188, 16, v189
	v_and_b32_e32 v189, 0xffff0000, v189
	v_lshlrev_b32_e32 v234, 16, v190
	v_and_b32_e32 v235, 0xffff0000, v190
	v_lshlrev_b32_e32 v190, 16, v191
	v_and_b32_e32 v191, 0xffff0000, v191
	v_lshlrev_b64 v[218:219], 1, v[200:201]
	s_andn2_b64 vcc, exec, s[34:35]
	s_waitcnt vmcnt(11)
	v_pk_fma_f32 v[186:187], v[114:115], v[186:187], v[126:127]
	s_waitcnt vmcnt(10)
	v_pk_fma_f32 v[184:185], v[130:131], v[184:185], v[138:139]
	v_pk_fma_f32 v[208:209], v[128:129], v[208:209], v[136:137]
	s_waitcnt vmcnt(6)
	v_pk_fma_f32 v[236:237], v[118:119], v[210:211], v[134:135] op_sel_hi:[1,0,1]
	v_pk_fma_f32 v[238:239], v[116:117], v[210:211], v[132:133] op_sel_hi:[1,0,1]
	v_pk_fma_f32 v[158:159], v[158:159], v[206:207], v[236:237] op_sel:[0,1,0]
	v_pk_fma_f32 v[156:157], v[156:157], v[206:207], v[238:239] op_sel:[0,1,0]
	v_pk_fma_f32 v[236:237], v[106:107], v[210:211], v[110:111] op_sel_hi:[1,0,1]
	v_pk_fma_f32 v[238:239], v[104:105], v[210:211], v[108:109] op_sel_hi:[1,0,1]
	v_pk_fma_f32 v[212:213], v[112:113], v[212:213], v[124:125]
	v_pk_fma_f32 v[238:239], v[152:153], v[206:207], v[238:239] op_sel:[0,1,0]
	v_pk_fma_f32 v[206:207], v[154:155], v[206:207], v[236:237] op_sel:[0,1,0]
	v_pk_mul_f32 v[152:153], v[158:159], s[52:53] op_sel_hi:[1,0]
	v_pk_mul_f32 v[154:155], v[156:157], s[52:53] op_sel_hi:[1,0]
	v_exp_f32_e32 v152, v152
	v_exp_f32_e32 v154, v154
	v_exp_f32_e32 v155, v155
	v_exp_f32_e32 v153, v153
	v_pk_mul_f32 v[158:159], v[238:239], s[52:53] op_sel_hi:[1,0]
	v_pk_add_f32 v[154:155], v[154:155], 1.0 op_sel_hi:[1,0]
	v_pk_add_f32 v[152:153], v[152:153], 1.0 op_sel_hi:[1,0]
	v_rcp_f32_e32 v154, v154
	v_rcp_f32_e32 v155, v155
	v_rcp_f32_e32 v156, v152
	v_rcp_f32_e32 v157, v153
	v_exp_f32_e32 v158, v158
	v_pk_fma_f32 v[152:153], v[154:155], v[232:233], v[208:209]
	v_exp_f32_e32 v159, v159
	v_pk_fma_f32 v[154:155], v[156:157], v[188:189], v[184:185]
	v_pk_mul_f32 v[156:157], v[206:207], s[52:53] op_sel_hi:[1,0]
	v_pk_add_f32 v[158:159], v[158:159], 1.0 op_sel_hi:[1,0]
	v_exp_f32_e32 v156, v156
	v_exp_f32_e32 v157, v157
	v_rcp_f32_e32 v158, v158
	v_rcp_f32_e32 v159, v159
	v_pk_add_f32 v[156:157], v[156:157], 1.0 op_sel_hi:[1,0]
	s_nop 0
	v_rcp_f32_e32 v184, v156
	v_rcp_f32_e32 v185, v157
	v_pk_fma_f32 v[156:157], v[158:159], v[234:235], v[212:213]
	v_pk_fma_f32 v[158:159], v[184:185], v[190:191], v[186:187]
	v_cndmask_b32_e64 v184, 0, 1, s[34:35]
	v_cmp_ne_u32_e64 s[4:5], 1, v184
	v_lshl_add_u64 v[184:185], s[10:11], 0, v[218:219]
	s_cbranch_vccnz .LBB0_1424
	global_store_dwordx4 v[184:185], v[152:155], off nt
	global_store_dwordx4 v[184:185], v[156:159], off offset:16 nt
	s_cbranch_execnz .LBB0_1376

.LBB0_1379:
	s_nop 1
	s_nop 0
	ds_read_b64 v[176:177], v205 offset:256
	s_nop 0
	s_nop 0
	s_nop 0
	s_nop 0
	s_waitcnt lgkmcnt(0)
	v_mul_f32_e64 v188, v177, -v176
	s_nop 0
	s_nop 0
	v_add_co_u32_e32 v144, vcc, 0x90000, v222
	v_pk_fma_f32 v[190:191], v[118:119], v[188:189], v[134:135] op_sel_hi:[1,0,1]
	s_nop 0
	v_addc_co_u32_e32 v145, vcc, 0, v223, vcc
	v_add_co_u32_e32 v148, vcc, 0x90000, v220
	global_load_dwordx4 v[144:147], v[144:145], off
	s_nop 0
	v_addc_co_u32_e32 v149, vcc, 0, v221, vcc
	global_load_dwordx4 v[148:151], v[148:149], off
	v_pk_fma_f32 v[142:143], v[142:143], v[176:177], v[190:191] op_sel:[0,1,0]
	s_waitcnt vmcnt(9)
	v_lshlrev_b32_e32 v178, 16, v168
	v_pk_mul_f32 v[142:143], v[142:143], s[52:53] op_sel_hi:[1,0]
	v_and_b32_e32 v179, 0xffff0000, v168
	v_exp_f32_e32 v142, v142
	v_exp_f32_e32 v143, v143
	v_lshlrev_b32_e32 v168, 16, v169
	v_and_b32_e32 v169, 0xffff0000, v169
	v_lshlrev_b32_e32 v180, 16, v170
	v_and_b32_e32 v181, 0xffff0000, v170
	v_lshlrev_b32_e32 v170, 16, v171
	v_and_b32_e32 v171, 0xffff0000, v171
	v_pk_fma_f32 v[168:169], v[176:177], v[168:169], v[188:189] op_sel:[1,0,0] op_sel_hi:[1,1,0]
	v_pk_fma_f32 v[178:179], v[176:177], v[178:179], v[188:189] op_sel:[1,0,0] op_sel_hi:[1,1,0]
	v_pk_fma_f32 v[170:171], v[176:177], v[170:171], v[188:189] op_sel:[1,0,0] op_sel_hi:[1,1,0]
	v_pk_fma_f32 v[180:181], v[176:177], v[180:181], v[188:189] op_sel:[1,0,0] op_sel_hi:[1,1,0]
	v_pk_fma_f32 v[206:207], v[116:117], v[188:189], v[132:133] op_sel_hi:[1,0,1]
	v_pk_fma_f32 v[190:191], v[106:107], v[188:189], v[110:111] op_sel_hi:[1,0,1]
	v_pk_fma_f32 v[188:189], v[104:105], v[188:189], v[108:109] op_sel_hi:[1,0,1]
	v_pk_fma_f32 v[140:141], v[140:141], v[176:177], v[206:207] op_sel:[0,1,0]
	v_pk_fma_f32 v[122:123], v[122:123], v[176:177], v[190:191] op_sel:[0,1,0]
	v_pk_fma_f32 v[120:121], v[120:121], v[176:177], v[188:189] op_sel:[0,1,0]
	v_pk_mul_f32 v[140:141], v[140:141], s[52:53] op_sel_hi:[1,0]
	v_pk_add_f32 v[142:143], v[142:143], 1.0 op_sel_hi:[1,0]
	v_pk_mul_f32 v[122:123], v[122:123], s[52:53] op_sel_hi:[1,0]
	v_pk_mul_f32 v[120:121], v[120:121], s[52:53] op_sel_hi:[1,0]
	v_exp_f32_e32 v140, v140
	v_exp_f32_e32 v141, v141
	v_rcp_f32_e32 v142, v142
	v_rcp_f32_e32 v143, v143
	v_exp_f32_e32 v120, v120
	v_exp_f32_e32 v176, v122
	v_exp_f32_e32 v177, v123
	v_exp_f32_e32 v121, v121
	s_waitcnt vmcnt(8)
	v_lshlrev_b32_e32 v182, 16, v172
	v_and_b32_e32 v183, 0xffff0000, v172
	v_lshlrev_b32_e32 v172, 16, v173
	v_and_b32_e32 v173, 0xffff0000, v173
	v_pk_fma_f32 v[168:169], v[130:131], v[168:169], v[138:139]
	v_pk_add_f32 v[140:141], v[140:141], 1.0 op_sel_hi:[1,0]
	v_pk_fma_f32 v[122:123], v[142:143], v[172:173], v[168:169]
	v_pk_add_f32 v[142:143], v[176:177], 1.0 op_sel_hi:[1,0]
	v_pk_add_f32 v[120:121], v[120:121], 1.0 op_sel_hi:[1,0]
	v_rcp_f32_e32 v140, v140
	v_rcp_f32_e32 v141, v141
	v_rcp_f32_e32 v142, v142
	v_rcp_f32_e32 v143, v143
	v_rcp_f32_e32 v168, v120
	v_rcp_f32_e32 v169, v121
	v_lshlrev_b32_e32 v186, 16, v174
	v_and_b32_e32 v187, 0xffff0000, v174
	v_lshlrev_b32_e32 v174, 16, v175
	v_and_b32_e32 v175, 0xffff0000, v175
	v_pk_fma_f32 v[178:179], v[128:129], v[178:179], v[136:137]
	v_pk_fma_f32 v[180:181], v[112:113], v[180:181], v[124:125]
	v_pk_fma_f32 v[170:171], v[114:115], v[170:171], v[126:127]
	v_pk_fma_f32 v[120:121], v[140:141], v[182:183], v[178:179]
	v_pk_fma_f32 v[142:143], v[142:143], v[174:175], v[170:171]
	s_and_b64 vcc, exec, s[4:5]
	v_pk_fma_f32 v[140:141], v[168:169], v[186:187], v[180:181]
	s_cbranch_vccnz .LBB0_1426
	v_lshl_add_u64 v[168:169], s[40:41], 0, v[218:219]
	global_store_dwordx4 v[168:169], v[120:123], off nt
	global_store_dwordx4 v[168:169], v[140:143], off offset:16 nt
	s_cbranch_execnz .LBB0_1382

.LBB0_1382:
	ds_read_b64 v[120:121], v205 offset:384
	s_nop 0
	s_waitcnt vmcnt(8)
	v_lshlrev_b32_e32 v122, 16, v160
	v_and_b32_e32 v123, 0xffff0000, v160
	v_lshlrev_b32_e32 v140, 16, v161
	v_and_b32_e32 v141, 0xffff0000, v161
	s_waitcnt lgkmcnt(0)
	v_mul_f32_e64 v170, v121, -v120
	v_pk_fma_f32 v[172:173], v[118:119], v[170:171], v[134:135] op_sel_hi:[1,0,1]
	v_lshlrev_b32_e32 v142, 16, v162
	v_pk_fma_f32 v[102:103], v[102:103], v[120:121], v[172:173] op_sel:[0,1,0]
	v_and_b32_e32 v143, 0xffff0000, v162
	v_pk_mul_f32 v[102:103], v[102:103], s[52:53] op_sel_hi:[1,0]
	v_lshlrev_b32_e32 v160, 16, v163
	v_exp_f32_e32 v102, v102
	v_exp_f32_e32 v103, v103
	v_and_b32_e32 v161, 0xffff0000, v163
	v_pk_fma_f32 v[140:141], v[120:121], v[140:141], v[170:171] op_sel:[1,0,0] op_sel_hi:[1,1,0]
	v_pk_fma_f32 v[122:123], v[120:121], v[122:123], v[170:171] op_sel:[1,0,0] op_sel_hi:[1,1,0]
	v_pk_fma_f32 v[160:161], v[120:121], v[160:161], v[170:171] op_sel:[1,0,0] op_sel_hi:[1,1,0]
	v_pk_fma_f32 v[142:143], v[120:121], v[142:143], v[170:171] op_sel:[1,0,0] op_sel_hi:[1,1,0]
	v_pk_fma_f32 v[174:175], v[116:117], v[170:171], v[132:133] op_sel_hi:[1,0,1]
	v_pk_fma_f32 v[172:173], v[106:107], v[170:171], v[110:111] op_sel_hi:[1,0,1]
	v_pk_fma_f32 v[170:171], v[104:105], v[170:171], v[108:109] op_sel_hi:[1,0,1]
	v_pk_fma_f32 v[100:101], v[100:101], v[120:121], v[174:175] op_sel:[0,1,0]
	v_pk_fma_f32 v[98:99], v[98:99], v[120:121], v[172:173] op_sel:[0,1,0]
	v_pk_fma_f32 v[96:97], v[96:97], v[120:121], v[170:171] op_sel:[0,1,0]
	v_pk_mul_f32 v[100:101], v[100:101], s[52:53] op_sel_hi:[1,0]
	v_pk_add_f32 v[102:103], v[102:103], 1.0 op_sel_hi:[1,0]
	v_pk_mul_f32 v[98:99], v[98:99], s[52:53] op_sel_hi:[1,0]
	v_pk_mul_f32 v[96:97], v[96:97], s[52:53] op_sel_hi:[1,0]
	v_exp_f32_e32 v100, v100
	v_exp_f32_e32 v101, v101
	v_rcp_f32_e32 v102, v102
	v_rcp_f32_e32 v103, v103
	v_exp_f32_e32 v96, v96
	v_exp_f32_e32 v120, v98
	v_exp_f32_e32 v121, v99
	v_exp_f32_e32 v97, v97
	s_nop 0
	s_waitcnt vmcnt(7)
	v_lshlrev_b32_e32 v162, 16, v164
	v_and_b32_e32 v163, 0xffff0000, v164
	v_lshlrev_b32_e32 v164, 16, v165
	v_and_b32_e32 v165, 0xffff0000, v165
	v_pk_fma_f32 v[140:141], v[130:131], v[140:141], v[138:139]
	v_pk_add_f32 v[100:101], v[100:101], 1.0 op_sel_hi:[1,0]
	v_pk_fma_f32 v[98:99], v[102:103], v[164:165], v[140:141]
	v_pk_add_f32 v[102:103], v[120:121], 1.0 op_sel_hi:[1,0]
	v_pk_add_f32 v[96:97], v[96:97], 1.0 op_sel_hi:[1,0]
	v_rcp_f32_e32 v100, v100
	v_rcp_f32_e32 v101, v101
	v_rcp_f32_e32 v102, v102
	v_rcp_f32_e32 v103, v103
	v_rcp_f32_e32 v120, v96
	v_rcp_f32_e32 v121, v97
	v_lshlrev_b32_e32 v168, 16, v166
	v_and_b32_e32 v169, 0xffff0000, v166
	v_lshlrev_b32_e32 v166, 16, v167
	v_and_b32_e32 v167, 0xffff0000, v167
	v_pk_fma_f32 v[122:123], v[128:129], v[122:123], v[136:137]
	v_pk_fma_f32 v[142:143], v[112:113], v[142:143], v[124:125]
	v_pk_fma_f32 v[160:161], v[114:115], v[160:161], v[126:127]
	v_pk_fma_f32 v[96:97], v[100:101], v[162:163], v[122:123]
	v_pk_fma_f32 v[102:103], v[102:103], v[166:167], v[160:161]
	s_and_b64 vcc, exec, s[4:5]
	v_pk_fma_f32 v[100:101], v[120:121], v[168:169], v[142:143]
	s_cbranch_vccnz .LBB0_1427
	v_lshl_add_u64 v[120:121], s[86:87], 0, v[218:219]
	global_store_dwordx4 v[120:121], v[96:99], off nt
	global_store_dwordx4 v[120:121], v[100:103], off offset:16 nt
	s_cbranch_execnz .LBB0_1385

.LBB0_1385:
	s_add_u32 s98, s28, 0x10000
	s_addc_u32 s99, s29, 0
	global_load_dwordx4 v[186:189], v200, s[98:99] offset:256
	s_add_u32 s98, s16, 0x0
	s_addc_u32 s99, s17, 0
	global_load_dwordx4 v[180:183], v200, s[98:99] offset:256
	s_add_u32 s98, s28, 0x0
	s_addc_u32 s99, s29, 0
	global_load_dwordx4 v[176:179], v200, s[98:99] offset:256
	s_nop 1
	v_add_co_u32_e32 v96, vcc, 0xa0000, v222
	s_nop 0
	s_waitcnt vmcnt(9)
	v_lshlrev_b32_e32 v98, 16, v246
	v_addc_co_u32_e32 v97, vcc, 0, v223, vcc
	global_load_dwordx4 v[160:163], v[96:97], off
	v_add_co_u32_e32 v96, vcc, 0xa0000, v220
	v_and_b32_e32 v99, 0xffff0000, v246
	s_nop 0
	v_addc_co_u32_e32 v97, vcc, 0, v221, vcc
	global_load_dwordx4 v[164:167], v[96:97], off
	v_add_co_u32_e32 v96, vcc, 0xb0000, v222
	v_lshlrev_b32_e32 v100, 16, v247
	s_nop 0
	v_addc_co_u32_e32 v97, vcc, 0, v223, vcc
	global_load_dwordx4 v[120:123], v[96:97], off
	v_add_co_u32_e32 v96, vcc, 0xb0000, v220
	v_and_b32_e32 v101, 0xffff0000, v247
	s_nop 0
	v_addc_co_u32_e32 v97, vcc, 0, v221, vcc
	global_load_dwordx4 v[140:143], v[96:97], off
	ds_read_b64 v[96:97], v205 offset:1024
	v_lshlrev_b32_e32 v102, 16, v248
	v_and_b32_e32 v103, 0xffff0000, v248
	v_lshlrev_b32_e32 v152, 16, v249
	v_and_b32_e32 v153, 0xffff0000, v249
	s_waitcnt lgkmcnt(0)
	v_mul_f32_e64 v170, v97, -v96
	v_pk_fma_f32 v[172:173], v[118:119], v[170:171], v[134:135] op_sel_hi:[1,0,1]
	v_pk_fma_f32 v[100:101], v[96:97], v[100:101], v[170:171] op_sel:[1,0,0] op_sel_hi:[1,1,0]
	v_pk_fma_f32 v[94:95], v[94:95], v[96:97], v[172:173] op_sel:[0,1,0]
	v_pk_fma_f32 v[98:99], v[96:97], v[98:99], v[170:171] op_sel:[1,0,0] op_sel_hi:[1,1,0]
	v_pk_mul_f32 v[94:95], v[94:95], s[52:53] op_sel_hi:[1,0]
	v_pk_fma_f32 v[152:153], v[96:97], v[152:153], v[170:171] op_sel:[1,0,0] op_sel_hi:[1,1,0]
	v_exp_f32_e32 v94, v94
	v_exp_f32_e32 v95, v95
	v_pk_fma_f32 v[102:103], v[96:97], v[102:103], v[170:171] op_sel:[1,0,0] op_sel_hi:[1,1,0]
	v_pk_fma_f32 v[174:175], v[116:117], v[170:171], v[132:133] op_sel_hi:[1,0,1]
	v_pk_fma_f32 v[172:173], v[106:107], v[170:171], v[110:111] op_sel_hi:[1,0,1]
	v_pk_fma_f32 v[170:171], v[104:105], v[170:171], v[108:109] op_sel_hi:[1,0,1]
	v_pk_fma_f32 v[92:93], v[92:93], v[96:97], v[174:175] op_sel:[0,1,0]
	v_pk_fma_f32 v[90:91], v[90:91], v[96:97], v[172:173] op_sel:[0,1,0]
	v_pk_fma_f32 v[88:89], v[88:89], v[96:97], v[170:171] op_sel:[0,1,0]
	v_pk_mul_f32 v[92:93], v[92:93], s[52:53] op_sel_hi:[1,0]
	v_pk_add_f32 v[94:95], v[94:95], 1.0 op_sel_hi:[1,0]
	v_pk_mul_f32 v[90:91], v[90:91], s[52:53] op_sel_hi:[1,0]
	v_pk_mul_f32 v[88:89], v[88:89], s[52:53] op_sel_hi:[1,0]
	v_exp_f32_e32 v92, v92
	v_exp_f32_e32 v93, v93
	v_rcp_f32_e32 v94, v94
	v_rcp_f32_e32 v95, v95
	v_exp_f32_e32 v88, v88
	v_exp_f32_e32 v96, v90
	v_exp_f32_e32 v97, v91
	v_exp_f32_e32 v89, v89
	s_nop 0
	v_lshlrev_b32_e32 v154, 16, v250
	v_and_b32_e32 v155, 0xffff0000, v250
	v_lshlrev_b32_e32 v250, 16, v251
	v_and_b32_e32 v251, 0xffff0000, v251
	v_pk_fma_f32 v[100:101], v[130:131], v[100:101], v[138:139]
	v_pk_add_f32 v[92:93], v[92:93], 1.0 op_sel_hi:[1,0]
	v_pk_fma_f32 v[90:91], v[94:95], v[250:251], v[100:101]
	v_pk_add_f32 v[94:95], v[96:97], 1.0 op_sel_hi:[1,0]
	v_pk_add_f32 v[88:89], v[88:89], 1.0 op_sel_hi:[1,0]
	v_rcp_f32_e32 v92, v92
	v_rcp_f32_e32 v93, v93
	v_rcp_f32_e32 v94, v94
	v_rcp_f32_e32 v95, v95
	v_rcp_f32_e32 v96, v88
	v_rcp_f32_e32 v97, v89
	v_lshlrev_b32_e32 v168, 16, v252
	v_and_b32_e32 v169, 0xffff0000, v252
	v_lshlrev_b32_e32 v252, 16, v253
	v_and_b32_e32 v253, 0xffff0000, v253
	v_pk_fma_f32 v[98:99], v[128:129], v[98:99], v[136:137]
	v_pk_fma_f32 v[102:103], v[112:113], v[102:103], v[124:125]
	v_pk_fma_f32 v[152:153], v[114:115], v[152:153], v[126:127]
	v_pk_fma_f32 v[88:89], v[92:93], v[154:155], v[98:99]
	v_pk_fma_f32 v[94:95], v[94:95], v[252:253], v[152:153]
	s_and_b64 vcc, exec, s[4:5]
	v_pk_fma_f32 v[92:93], v[96:97], v[168:169], v[102:103]
	s_cbranch_vccnz .LBB0_1428
	v_lshl_add_u64 v[96:97], s[96:97], 0, v[218:219]
	global_store_dwordx4 v[96:97], v[88:91], off nt
	global_store_dwordx4 v[96:97], v[92:95], off offset:16 nt
	s_cbranch_execnz .LBB0_1388

.LBB0_1388:
	ds_read_b64 v[88:89], v205 offset:1152
	s_nop 0
	s_waitcnt vmcnt(11)
	v_lshlrev_b32_e32 v94, 16, v146
	v_and_b32_e32 v95, 0xffff0000, v146
	s_nop 0
	s_waitcnt vmcnt(10)
	v_lshlrev_b32_e32 v98, 16, v148
	v_and_b32_e32 v99, 0xffff0000, v148
	s_waitcnt lgkmcnt(0)
	v_mul_f32_e64 v146, v89, -v88
	v_lshlrev_b32_e32 v100, 16, v149
	v_and_b32_e32 v101, 0xffff0000, v149
	v_pk_fma_f32 v[148:149], v[118:119], v[146:147], v[134:135] op_sel_hi:[1,0,1]
	v_lshlrev_b32_e32 v90, 16, v144
	v_pk_fma_f32 v[86:87], v[86:87], v[88:89], v[148:149] op_sel:[0,1,0]
	v_and_b32_e32 v91, 0xffff0000, v144
	v_pk_mul_f32 v[86:87], v[86:87], s[52:53] op_sel_hi:[1,0]
	v_lshlrev_b32_e32 v92, 16, v145
	v_exp_f32_e32 v86, v86
	v_exp_f32_e32 v87, v87
	v_and_b32_e32 v93, 0xffff0000, v145
	v_lshlrev_b32_e32 v96, 16, v147
	v_and_b32_e32 v97, 0xffff0000, v147
	v_lshlrev_b32_e32 v102, 16, v150
	v_and_b32_e32 v103, 0xffff0000, v150
	v_lshlrev_b32_e32 v144, 16, v151
	v_and_b32_e32 v145, 0xffff0000, v151
	v_pk_fma_f32 v[92:93], v[88:89], v[92:93], v[146:147] op_sel:[1,0,0] op_sel_hi:[1,1,0]
	v_pk_fma_f32 v[90:91], v[88:89], v[90:91], v[146:147] op_sel:[1,0,0] op_sel_hi:[1,1,0]
	v_pk_fma_f32 v[96:97], v[88:89], v[96:97], v[146:147] op_sel:[1,0,0] op_sel_hi:[1,1,0]
	v_pk_fma_f32 v[94:95], v[88:89], v[94:95], v[146:147] op_sel:[1,0,0] op_sel_hi:[1,1,0]
	v_pk_fma_f32 v[150:151], v[116:117], v[146:147], v[132:133] op_sel_hi:[1,0,1]
	v_pk_fma_f32 v[148:149], v[106:107], v[146:147], v[110:111] op_sel_hi:[1,0,1]
	v_pk_fma_f32 v[146:147], v[104:105], v[146:147], v[108:109] op_sel_hi:[1,0,1]
	v_pk_fma_f32 v[84:85], v[84:85], v[88:89], v[150:151] op_sel:[0,1,0]
	v_pk_fma_f32 v[82:83], v[82:83], v[88:89], v[148:149] op_sel:[0,1,0]
	v_pk_fma_f32 v[80:81], v[80:81], v[88:89], v[146:147] op_sel:[0,1,0]
	v_pk_mul_f32 v[84:85], v[84:85], s[52:53] op_sel_hi:[1,0]
	v_pk_add_f32 v[86:87], v[86:87], 1.0 op_sel_hi:[1,0]
	v_pk_mul_f32 v[82:83], v[82:83], s[52:53] op_sel_hi:[1,0]
	v_pk_mul_f32 v[80:81], v[80:81], s[52:53] op_sel_hi:[1,0]
	v_exp_f32_e32 v84, v84
	v_exp_f32_e32 v85, v85
	v_rcp_f32_e32 v86, v86
	v_rcp_f32_e32 v87, v87
	v_exp_f32_e32 v80, v80
	v_exp_f32_e32 v88, v82
	v_exp_f32_e32 v89, v83
	v_exp_f32_e32 v81, v81
	v_pk_fma_f32 v[92:93], v[130:131], v[92:93], v[138:139]
	v_pk_add_f32 v[84:85], v[84:85], 1.0 op_sel_hi:[1,0]
	v_pk_fma_f32 v[82:83], v[86:87], v[100:101], v[92:93]
	v_pk_add_f32 v[86:87], v[88:89], 1.0 op_sel_hi:[1,0]
	v_pk_add_f32 v[80:81], v[80:81], 1.0 op_sel_hi:[1,0]
	v_rcp_f32_e32 v84, v84
	v_rcp_f32_e32 v85, v85
	v_rcp_f32_e32 v86, v86
	v_rcp_f32_e32 v87, v87
	v_rcp_f32_e32 v88, v80
	v_rcp_f32_e32 v89, v81
	v_pk_fma_f32 v[90:91], v[128:129], v[90:91], v[136:137]
	v_pk_fma_f32 v[94:95], v[112:113], v[94:95], v[124:125]
	v_pk_fma_f32 v[96:97], v[114:115], v[96:97], v[126:127]
	v_pk_fma_f32 v[80:81], v[84:85], v[98:99], v[90:91]
	v_pk_fma_f32 v[86:87], v[86:87], v[144:145], v[96:97]
	s_and_b64 vcc, exec, s[4:5]
	v_pk_fma_f32 v[84:85], v[88:89], v[102:103], v[94:95]
	s_cbranch_vccnz .LBB0_1429
	v_lshl_add_u64 v[88:89], s[92:93], 0, v[218:219]
	global_store_dwordx4 v[88:89], v[80:83], off nt
	global_store_dwordx4 v[88:89], v[84:87], off offset:16 nt
	s_cbranch_execnz .LBB0_1391

.LBB0_1391:
	s_add_u32 s98, s16, 0x30000
	s_addc_u32 s99, s17, 0
	global_load_dwordx4 v[172:175], v200, s[98:99] offset:256
	s_add_u32 s98, s28, 0x30000
	s_addc_u32 s99, s29, 0
	global_load_dwordx4 v[168:171], v200, s[98:99] offset:256
	s_add_u32 s98, s16, 0x20000
	s_addc_u32 s99, s17, 0
	global_load_dwordx4 v[148:151], v200, s[98:99] offset:256
	s_add_u32 s98, s28, 0x20000
	s_addc_u32 s99, s29, 0
	global_load_dwordx4 v[144:147], v200, s[98:99] offset:256
	s_nop 1
	s_nop 0
	s_nop 0
	s_nop 0
	s_nop 0
	s_nop 0
	v_add_co_u32_e32 v80, vcc, 0x10000, v220
	s_nop 0
	s_waitcnt vmcnt(9)
	v_lshlrev_b32_e32 v82, 16, v160
	v_addc_co_u32_e32 v81, vcc, 0, v221, vcc
	global_load_dwordx4 v[100:103], v[80:81], off offset:256
	ds_read_b64 v[80:81], v205 offset:1280
	v_and_b32_e32 v83, 0xffff0000, v160
	v_lshlrev_b32_e32 v84, 16, v161
	v_and_b32_e32 v85, 0xffff0000, v161
	v_lshlrev_b32_e32 v86, 16, v162
	s_waitcnt lgkmcnt(0)
	v_mul_f32_e64 v154, v81, -v80
	v_pk_fma_f32 v[156:157], v[118:119], v[154:155], v[134:135] op_sel_hi:[1,0,1]
	v_and_b32_e32 v87, 0xffff0000, v162
	v_pk_fma_f32 v[78:79], v[78:79], v[80:81], v[156:157] op_sel:[0,1,0]
	v_lshlrev_b32_e32 v88, 16, v163
	v_pk_mul_f32 v[78:79], v[78:79], s[52:53] op_sel_hi:[1,0]
	v_and_b32_e32 v89, 0xffff0000, v163
	v_exp_f32_e32 v78, v78
	v_exp_f32_e32 v79, v79
	v_pk_fma_f32 v[84:85], v[80:81], v[84:85], v[154:155] op_sel:[1,0,0] op_sel_hi:[1,1,0]
	v_pk_fma_f32 v[82:83], v[80:81], v[82:83], v[154:155] op_sel:[1,0,0] op_sel_hi:[1,1,0]
	v_pk_fma_f32 v[88:89], v[80:81], v[88:89], v[154:155] op_sel:[1,0,0] op_sel_hi:[1,1,0]
	v_pk_fma_f32 v[86:87], v[80:81], v[86:87], v[154:155] op_sel:[1,0,0] op_sel_hi:[1,1,0]
	v_pk_fma_f32 v[158:159], v[116:117], v[154:155], v[132:133] op_sel_hi:[1,0,1]
	v_pk_fma_f32 v[156:157], v[106:107], v[154:155], v[110:111] op_sel_hi:[1,0,1]
	v_pk_fma_f32 v[154:155], v[104:105], v[154:155], v[108:109] op_sel_hi:[1,0,1]
	v_pk_fma_f32 v[76:77], v[76:77], v[80:81], v[158:159] op_sel:[0,1,0]
	v_pk_fma_f32 v[74:75], v[74:75], v[80:81], v[156:157] op_sel:[0,1,0]
	v_pk_fma_f32 v[72:73], v[72:73], v[80:81], v[154:155] op_sel:[0,1,0]
	v_pk_mul_f32 v[76:77], v[76:77], s[52:53] op_sel_hi:[1,0]
	v_pk_add_f32 v[78:79], v[78:79], 1.0 op_sel_hi:[1,0]
	v_pk_mul_f32 v[74:75], v[74:75], s[52:53] op_sel_hi:[1,0]
	v_pk_mul_f32 v[72:73], v[72:73], s[52:53] op_sel_hi:[1,0]
	v_exp_f32_e32 v76, v76
	v_exp_f32_e32 v77, v77
	v_rcp_f32_e32 v78, v78
	v_rcp_f32_e32 v79, v79
	v_exp_f32_e32 v72, v72
	v_exp_f32_e32 v80, v74
	v_exp_f32_e32 v81, v75
	v_exp_f32_e32 v73, v73
	s_nop 0
	s_waitcnt vmcnt(9)
	v_lshlrev_b32_e32 v92, 16, v165
	v_and_b32_e32 v93, 0xffff0000, v165
	v_pk_fma_f32 v[84:85], v[130:131], v[84:85], v[138:139]
	v_pk_add_f32 v[76:77], v[76:77], 1.0 op_sel_hi:[1,0]
	v_pk_fma_f32 v[74:75], v[78:79], v[92:93], v[84:85]
	v_pk_add_f32 v[78:79], v[80:81], 1.0 op_sel_hi:[1,0]
	v_pk_add_f32 v[72:73], v[72:73], 1.0 op_sel_hi:[1,0]
	v_rcp_f32_e32 v76, v76
	v_rcp_f32_e32 v77, v77
	v_rcp_f32_e32 v78, v78
	v_rcp_f32_e32 v79, v79
	v_rcp_f32_e32 v80, v72
	v_rcp_f32_e32 v81, v73
	v_lshlrev_b32_e32 v90, 16, v164
	v_and_b32_e32 v91, 0xffff0000, v164
	v_lshlrev_b32_e32 v94, 16, v166
	v_and_b32_e32 v95, 0xffff0000, v166
	v_lshlrev_b32_e32 v152, 16, v167
	v_and_b32_e32 v153, 0xffff0000, v167
	v_pk_fma_f32 v[82:83], v[128:129], v[82:83], v[136:137]
	v_pk_fma_f32 v[86:87], v[112:113], v[86:87], v[124:125]
	v_pk_fma_f32 v[88:89], v[114:115], v[88:89], v[126:127]
	v_pk_fma_f32 v[72:73], v[76:77], v[90:91], v[82:83]
	v_pk_fma_f32 v[78:79], v[78:79], v[152:153], v[88:89]
	s_and_b64 vcc, exec, s[4:5]
	v_pk_fma_f32 v[76:77], v[80:81], v[94:95], v[86:87]
	s_cbranch_vccnz .LBB0_1430
	v_lshl_add_u64 v[80:81], s[88:89], 0, v[218:219]
	global_store_dwordx4 v[80:81], v[72:75], off nt
	global_store_dwordx4 v[80:81], v[76:79], off offset:16 nt
	s_cbranch_execnz .LBB0_1394

.LBB0_1394:
	ds_read_b64 v[72:73], v205 offset:1408
	s_nop 0
	s_waitcnt vmcnt(9)
	v_lshlrev_b32_e32 v74, 16, v120
	v_and_b32_e32 v75, 0xffff0000, v120
	v_lshlrev_b32_e32 v76, 16, v121
	v_and_b32_e32 v77, 0xffff0000, v121
	s_waitcnt lgkmcnt(0)
	v_mul_f32_e64 v90, v73, -v72
	v_pk_fma_f32 v[92:93], v[118:119], v[90:91], v[134:135] op_sel_hi:[1,0,1]
	v_lshlrev_b32_e32 v78, 16, v122
	v_pk_fma_f32 v[70:71], v[70:71], v[72:73], v[92:93] op_sel:[0,1,0]
	v_and_b32_e32 v79, 0xffff0000, v122
	v_pk_mul_f32 v[70:71], v[70:71], s[52:53] op_sel_hi:[1,0]
	v_lshlrev_b32_e32 v80, 16, v123
	v_exp_f32_e32 v70, v70
	v_exp_f32_e32 v71, v71
	v_and_b32_e32 v81, 0xffff0000, v123
	v_pk_fma_f32 v[76:77], v[72:73], v[76:77], v[90:91] op_sel:[1,0,0] op_sel_hi:[1,1,0]
	v_pk_fma_f32 v[74:75], v[72:73], v[74:75], v[90:91] op_sel:[1,0,0] op_sel_hi:[1,1,0]
	v_pk_fma_f32 v[80:81], v[72:73], v[80:81], v[90:91] op_sel:[1,0,0] op_sel_hi:[1,1,0]
	v_pk_fma_f32 v[78:79], v[72:73], v[78:79], v[90:91] op_sel:[1,0,0] op_sel_hi:[1,1,0]
	v_pk_fma_f32 v[94:95], v[116:117], v[90:91], v[132:133] op_sel_hi:[1,0,1]
	v_pk_fma_f32 v[92:93], v[106:107], v[90:91], v[110:111] op_sel_hi:[1,0,1]
	v_pk_fma_f32 v[90:91], v[104:105], v[90:91], v[108:109] op_sel_hi:[1,0,1]
	v_pk_fma_f32 v[68:69], v[68:69], v[72:73], v[94:95] op_sel:[0,1,0]
	v_pk_fma_f32 v[66:67], v[66:67], v[72:73], v[92:93] op_sel:[0,1,0]
	v_pk_fma_f32 v[64:65], v[64:65], v[72:73], v[90:91] op_sel:[0,1,0]
	v_pk_mul_f32 v[68:69], v[68:69], s[52:53] op_sel_hi:[1,0]
	v_pk_add_f32 v[70:71], v[70:71], 1.0 op_sel_hi:[1,0]
	v_pk_mul_f32 v[66:67], v[66:67], s[52:53] op_sel_hi:[1,0]
	v_pk_mul_f32 v[64:65], v[64:65], s[52:53] op_sel_hi:[1,0]
	v_exp_f32_e32 v68, v68
	v_exp_f32_e32 v69, v69
	v_rcp_f32_e32 v70, v70
	v_rcp_f32_e32 v71, v71
	v_exp_f32_e32 v64, v64
	v_exp_f32_e32 v72, v66
	v_exp_f32_e32 v73, v67
	v_exp_f32_e32 v65, v65
	s_nop 0
	s_waitcnt vmcnt(8)
	v_lshlrev_b32_e32 v84, 16, v141
	v_and_b32_e32 v85, 0xffff0000, v141
	v_pk_fma_f32 v[76:77], v[130:131], v[76:77], v[138:139]
	v_pk_add_f32 v[68:69], v[68:69], 1.0 op_sel_hi:[1,0]
	v_pk_fma_f32 v[66:67], v[70:71], v[84:85], v[76:77]
	v_pk_add_f32 v[70:71], v[72:73], 1.0 op_sel_hi:[1,0]
	v_pk_add_f32 v[64:65], v[64:65], 1.0 op_sel_hi:[1,0]
	v_rcp_f32_e32 v68, v68
	v_rcp_f32_e32 v69, v69
	v_rcp_f32_e32 v70, v70
	v_rcp_f32_e32 v71, v71
	v_rcp_f32_e32 v72, v64
	v_rcp_f32_e32 v73, v65
	v_lshlrev_b32_e32 v82, 16, v140
	v_and_b32_e32 v83, 0xffff0000, v140
	v_lshlrev_b32_e32 v86, 16, v142
	v_and_b32_e32 v87, 0xffff0000, v142
	v_lshlrev_b32_e32 v88, 16, v143
	v_and_b32_e32 v89, 0xffff0000, v143
	v_pk_fma_f32 v[74:75], v[128:129], v[74:75], v[136:137]
	v_pk_fma_f32 v[78:79], v[112:113], v[78:79], v[124:125]
	v_pk_fma_f32 v[80:81], v[114:115], v[80:81], v[126:127]
	v_pk_fma_f32 v[64:65], v[68:69], v[82:83], v[74:75]
	v_pk_fma_f32 v[70:71], v[70:71], v[88:89], v[80:81]
	s_and_b64 vcc, exec, s[4:5]
	v_pk_fma_f32 v[68:69], v[72:73], v[86:87], v[78:79]
	s_cbranch_vccnz .LBB0_1431
	v_lshl_add_u64 v[72:73], s[90:91], 0, v[218:219]
	global_store_dwordx4 v[72:73], v[64:67], off nt
	global_store_dwordx4 v[72:73], v[68:71], off offset:16 nt
	s_cbranch_execnz .LBB0_1397

.LBB0_1397:
	v_or_b32_e32 v80, 0x80, v224
	v_ashrrev_i32_e32 v81, 31, v80
	v_lshl_add_u64 v[92:93], v[80:81], 2, s[26:27]
	global_load_dwordx4 v[72:75], v[226:227], off offset:528
	global_load_dwordx4 v[84:87], v[226:227], off offset:512
	global_load_dwordx4 v[76:79], v[228:229], off offset:528
	global_load_dwordx4 v[88:91], v[228:229], off offset:512
	global_load_dwordx4 v[64:67], v[230:231], off offset:528
	global_load_dwordx4 v[68:71], v[230:231], off offset:512
	global_load_dwordx4 v[80:83], v[92:93], off offset:16
	s_nop 0
	global_load_dwordx4 v[92:95], v[92:93], off
	s_add_u32 s98, s16, 0x90000
	s_addc_u32 s99, s17, 0
	global_load_dwordx4 v[160:163], v200, s[98:99] offset:256
	s_add_u32 s98, s28, 0x90000
	s_addc_u32 s99, s29, 0
	global_load_dwordx4 v[156:159], v200, s[98:99] offset:256
	s_add_u32 s98, s16, 0x80000
	s_addc_u32 s99, s17, 0
	global_load_dwordx4 v[152:155], v200, s[98:99] offset:256
	s_add_u32 s98, s28, 0x80000
	s_addc_u32 s99, s29, 0
	global_load_dwordx4 v[116:119], v200, s[98:99] offset:256
	s_nop 0
	ds_read_b64 v[120:121], v205
	s_nop 0
	s_nop 0
	s_nop 0
	s_nop 0
	s_waitcnt lgkmcnt(0)
	v_mul_f32_e64 v138, v121, -v120
	s_nop 0
	s_nop 0
	s_nop 0
	s_nop 0
	v_lshlrev_b32_e32 v122, 16, v176
	s_nop 0
	s_nop 0
	s_nop 0
	s_nop 0
	s_nop 0
	s_nop 0
	v_and_b32_e32 v123, 0xffff0000, v176
	v_lshlrev_b32_e32 v124, 16, v177
	v_and_b32_e32 v125, 0xffff0000, v177
	v_lshlrev_b32_e32 v126, 16, v178
	v_and_b32_e32 v127, 0xffff0000, v178
	v_lshlrev_b32_e32 v128, 16, v179
	v_and_b32_e32 v129, 0xffff0000, v179
	v_pk_fma_f32 v[124:125], v[120:121], v[124:125], v[138:139] op_sel:[1,0,0] op_sel_hi:[1,1,0]
	v_pk_fma_f32 v[122:123], v[120:121], v[122:123], v[138:139] op_sel:[1,0,0] op_sel_hi:[1,1,0]
	v_pk_fma_f32 v[128:129], v[120:121], v[128:129], v[138:139] op_sel:[1,0,0] op_sel_hi:[1,1,0]
	v_pk_fma_f32 v[126:127], v[120:121], v[126:127], v[138:139] op_sel:[1,0,0] op_sel_hi:[1,1,0]
	s_nop 0
	v_lshlrev_b32_e32 v130, 16, v180
	v_and_b32_e32 v131, 0xffff0000, v180
	v_lshlrev_b32_e32 v132, 16, v181
	v_and_b32_e32 v133, 0xffff0000, v181
	v_lshlrev_b32_e32 v134, 16, v182
	v_and_b32_e32 v135, 0xffff0000, v182
	v_lshlrev_b32_e32 v136, 16, v183
	v_and_b32_e32 v137, 0xffff0000, v183
	s_and_b64 vcc, exec, s[4:5]
	s_nop 0
	s_waitcnt vmcnt(9)
	v_pk_fma_f32 v[126:127], v[72:73], v[126:127], v[76:77]
	s_nop 0
	s_waitcnt vmcnt(8)
	v_pk_fma_f32 v[122:123], v[84:85], v[122:123], v[88:89]
	v_pk_fma_f32 v[124:125], v[86:87], v[124:125], v[90:91]
	v_pk_fma_f32 v[128:129], v[74:75], v[128:129], v[78:79]
	s_nop 0
	s_waitcnt vmcnt(4)
	v_pk_fma_f32 v[140:141], v[70:71], v[138:139], v[94:95] op_sel_hi:[1,0,1]
	v_pk_fma_f32 v[142:143], v[68:69], v[138:139], v[92:93] op_sel_hi:[1,0,1]
	v_pk_fma_f32 v[62:63], v[62:63], v[120:121], v[140:141] op_sel:[0,1,0]
	v_pk_fma_f32 v[60:61], v[60:61], v[120:121], v[142:143] op_sel:[0,1,0]
	v_pk_fma_f32 v[140:141], v[66:67], v[138:139], v[82:83] op_sel_hi:[1,0,1]
	v_pk_fma_f32 v[138:139], v[64:65], v[138:139], v[80:81] op_sel_hi:[1,0,1]
	v_pk_fma_f32 v[140:141], v[58:59], v[120:121], v[140:141] op_sel:[0,1,0]
	v_pk_fma_f32 v[120:121], v[56:57], v[120:121], v[138:139] op_sel:[0,1,0]
	v_pk_mul_f32 v[56:57], v[62:63], s[52:53] op_sel_hi:[1,0]
	v_pk_mul_f32 v[58:59], v[60:61], s[52:53] op_sel_hi:[1,0]
	v_exp_f32_e32 v56, v56
	v_exp_f32_e32 v58, v58
	v_exp_f32_e32 v59, v59
	v_exp_f32_e32 v57, v57
	v_pk_mul_f32 v[62:63], v[120:121], s[52:53] op_sel_hi:[1,0]
	v_pk_add_f32 v[58:59], v[58:59], 1.0 op_sel_hi:[1,0]
	v_pk_add_f32 v[56:57], v[56:57], 1.0 op_sel_hi:[1,0]
	v_rcp_f32_e32 v60, v58
	v_rcp_f32_e32 v61, v59
	v_rcp_f32_e32 v56, v56
	v_rcp_f32_e32 v57, v57
	v_exp_f32_e32 v62, v62
	v_exp_f32_e32 v63, v63
	v_pk_fma_f32 v[58:59], v[56:57], v[132:133], v[124:125]
	v_pk_fma_f32 v[56:57], v[60:61], v[130:131], v[122:123]
	v_pk_mul_f32 v[60:61], v[140:141], s[52:53] op_sel_hi:[1,0]
	v_pk_add_f32 v[62:63], v[62:63], 1.0 op_sel_hi:[1,0]
	v_exp_f32_e32 v60, v60
	v_exp_f32_e32 v61, v61
	v_rcp_f32_e32 v120, v62
	v_rcp_f32_e32 v121, v63
	v_pk_add_f32 v[60:61], v[60:61], 1.0 op_sel_hi:[1,0]
	s_nop 0
	v_rcp_f32_e32 v60, v60
	v_rcp_f32_e32 v61, v61
	s_nop 0
	v_pk_fma_f32 v[62:63], v[60:61], v[136:137], v[128:129]
	v_pk_fma_f32 v[60:61], v[120:121], v[134:135], v[126:127]
	s_cbranch_vccnz .LBB0_1432
	global_store_dwordx4 v[184:185], v[56:59], off offset:512 nt
	global_store_dwordx4 v[184:185], v[60:63], off offset:528 nt
	s_cbranch_execnz .LBB0_1400

.LBB0_1400:
	ds_read_b64 v[56:57], v205 offset:128
	s_nop 0
	v_lshlrev_b32_e32 v58, 16, v186
	v_and_b32_e32 v59, 0xffff0000, v186
	v_lshlrev_b32_e32 v60, 16, v187
	v_and_b32_e32 v61, 0xffff0000, v187
	s_waitcnt lgkmcnt(0)
	v_mul_f32_e64 v122, v57, -v56
	v_pk_fma_f32 v[124:125], v[70:71], v[122:123], v[94:95] op_sel_hi:[1,0,1]
	v_lshlrev_b32_e32 v62, 16, v188
	v_pk_fma_f32 v[54:55], v[54:55], v[56:57], v[124:125] op_sel:[0,1,0]
	v_and_b32_e32 v63, 0xffff0000, v188
	v_pk_mul_f32 v[54:55], v[54:55], s[52:53] op_sel_hi:[1,0]
	v_lshlrev_b32_e32 v96, 16, v189
	v_exp_f32_e32 v54, v54
	v_exp_f32_e32 v55, v55
	v_and_b32_e32 v97, 0xffff0000, v189
	v_pk_fma_f32 v[60:61], v[56:57], v[60:61], v[122:123] op_sel:[1,0,0] op_sel_hi:[1,1,0]
	v_pk_fma_f32 v[58:59], v[56:57], v[58:59], v[122:123] op_sel:[1,0,0] op_sel_hi:[1,1,0]
	v_pk_fma_f32 v[96:97], v[56:57], v[96:97], v[122:123] op_sel:[1,0,0] op_sel_hi:[1,1,0]
	v_pk_fma_f32 v[62:63], v[56:57], v[62:63], v[122:123] op_sel:[1,0,0] op_sel_hi:[1,1,0]
	v_pk_fma_f32 v[126:127], v[68:69], v[122:123], v[92:93] op_sel_hi:[1,0,1]
	v_pk_fma_f32 v[124:125], v[66:67], v[122:123], v[82:83] op_sel_hi:[1,0,1]
	v_pk_fma_f32 v[122:123], v[64:65], v[122:123], v[80:81] op_sel_hi:[1,0,1]
	v_pk_fma_f32 v[52:53], v[52:53], v[56:57], v[126:127] op_sel:[0,1,0]
	v_pk_fma_f32 v[50:51], v[50:51], v[56:57], v[124:125] op_sel:[0,1,0]
	v_pk_fma_f32 v[48:49], v[48:49], v[56:57], v[122:123] op_sel:[0,1,0]
	v_pk_mul_f32 v[52:53], v[52:53], s[52:53] op_sel_hi:[1,0]
	v_pk_add_f32 v[54:55], v[54:55], 1.0 op_sel_hi:[1,0]
	v_pk_mul_f32 v[50:51], v[50:51], s[52:53] op_sel_hi:[1,0]
	v_pk_mul_f32 v[48:49], v[48:49], s[52:53] op_sel_hi:[1,0]
	v_exp_f32_e32 v52, v52
	v_exp_f32_e32 v53, v53
	v_rcp_f32_e32 v54, v54
	v_rcp_f32_e32 v55, v55
	v_exp_f32_e32 v48, v48
	v_exp_f32_e32 v56, v50
	v_exp_f32_e32 v57, v51
	v_exp_f32_e32 v49, v49
	v_lshlrev_b32_e32 v98, 16, v100
	v_and_b32_e32 v99, 0xffff0000, v100
	v_lshlrev_b32_e32 v100, 16, v101
	v_and_b32_e32 v101, 0xffff0000, v101
	v_pk_fma_f32 v[60:61], v[86:87], v[60:61], v[90:91]
	v_pk_add_f32 v[52:53], v[52:53], 1.0 op_sel_hi:[1,0]
	v_pk_fma_f32 v[50:51], v[54:55], v[100:101], v[60:61]
	v_pk_add_f32 v[54:55], v[56:57], 1.0 op_sel_hi:[1,0]
	v_pk_add_f32 v[48:49], v[48:49], 1.0 op_sel_hi:[1,0]
	v_rcp_f32_e32 v52, v52
	v_rcp_f32_e32 v53, v53
	v_rcp_f32_e32 v54, v54
	v_rcp_f32_e32 v55, v55
	v_rcp_f32_e32 v56, v48
	v_rcp_f32_e32 v57, v49
	v_lshlrev_b32_e32 v120, 16, v102
	v_and_b32_e32 v121, 0xffff0000, v102
	v_lshlrev_b32_e32 v102, 16, v103
	v_and_b32_e32 v103, 0xffff0000, v103
	v_pk_fma_f32 v[58:59], v[84:85], v[58:59], v[88:89]
	v_pk_fma_f32 v[62:63], v[72:73], v[62:63], v[76:77]
	v_pk_fma_f32 v[96:97], v[74:75], v[96:97], v[78:79]
	v_pk_fma_f32 v[48:49], v[52:53], v[98:99], v[58:59]
	v_pk_fma_f32 v[54:55], v[54:55], v[102:103], v[96:97]
	s_and_b64 vcc, exec, s[4:5]
	v_pk_fma_f32 v[52:53], v[56:57], v[120:121], v[62:63]
	s_cbranch_vccnz .LBB0_1433
	v_lshl_add_u64 v[56:57], s[70:71], 0, v[218:219]
	global_store_dwordx4 v[56:57], v[48:51], off nt
	global_store_dwordx4 v[56:57], v[52:55], off offset:16 nt
	s_cbranch_execnz .LBB0_1403

.LBB0_1403:
	s_add_u32 s98, s16, 0xb0000
	s_addc_u32 s99, s17, 0
	global_load_dwordx4 v[136:139], v200, s[98:99] offset:256
	s_add_u32 s98, s28, 0xb0000
	s_addc_u32 s99, s29, 0
	global_load_dwordx4 v[132:135], v200, s[98:99] offset:256
	s_add_u32 s98, s16, 0xa0000
	s_addc_u32 s99, s17, 0
	global_load_dwordx4 v[128:131], v200, s[98:99] offset:256
	s_add_u32 s98, s28, 0xa0000
	s_addc_u32 s99, s29, 0
	global_load_dwordx4 v[52:55], v200, s[98:99] offset:256
	s_nop 1
	s_nop 0
	ds_read_b64 v[96:97], v205 offset:256
	s_nop 0
	s_nop 0
	s_nop 0
	s_nop 0
	s_waitcnt lgkmcnt(0)
	v_mul_f32_e64 v122, v97, -v96
	s_nop 0
	s_nop 0
	s_nop 0
	v_pk_fma_f32 v[124:125], v[70:71], v[122:123], v[94:95] op_sel_hi:[1,0,1]
	s_nop 0
	s_nop 0
	s_nop 0
	s_nop 0
	s_nop 0
	s_nop 0
	s_nop 0
	v_pk_fma_f32 v[46:47], v[46:47], v[96:97], v[124:125] op_sel:[0,1,0]
	s_nop 0
	v_lshlrev_b32_e32 v98, 16, v144
	v_pk_mul_f32 v[46:47], v[46:47], s[52:53] op_sel_hi:[1,0]
	v_and_b32_e32 v99, 0xffff0000, v144
	v_exp_f32_e32 v46, v46
	v_exp_f32_e32 v47, v47
	v_lshlrev_b32_e32 v100, 16, v145
	v_and_b32_e32 v101, 0xffff0000, v145
	v_lshlrev_b32_e32 v102, 16, v146
	v_and_b32_e32 v103, 0xffff0000, v146
	v_lshlrev_b32_e32 v112, 16, v147
	v_and_b32_e32 v113, 0xffff0000, v147
	v_pk_fma_f32 v[100:101], v[96:97], v[100:101], v[122:123] op_sel:[1,0,0] op_sel_hi:[1,1,0]
	v_pk_fma_f32 v[98:99], v[96:97], v[98:99], v[122:123] op_sel:[1,0,0] op_sel_hi:[1,1,0]
	v_pk_fma_f32 v[112:113], v[96:97], v[112:113], v[122:123] op_sel:[1,0,0] op_sel_hi:[1,1,0]
	v_pk_fma_f32 v[102:103], v[96:97], v[102:103], v[122:123] op_sel:[1,0,0] op_sel_hi:[1,1,0]
	v_pk_fma_f32 v[126:127], v[68:69], v[122:123], v[92:93] op_sel_hi:[1,0,1]
	v_pk_fma_f32 v[124:125], v[66:67], v[122:123], v[82:83] op_sel_hi:[1,0,1]
	v_pk_fma_f32 v[122:123], v[64:65], v[122:123], v[80:81] op_sel_hi:[1,0,1]
	v_pk_fma_f32 v[44:45], v[44:45], v[96:97], v[126:127] op_sel:[0,1,0]
	v_pk_fma_f32 v[42:43], v[42:43], v[96:97], v[124:125] op_sel:[0,1,0]
	v_pk_fma_f32 v[40:41], v[40:41], v[96:97], v[122:123] op_sel:[0,1,0]
	v_pk_mul_f32 v[44:45], v[44:45], s[52:53] op_sel_hi:[1,0]
	v_pk_add_f32 v[46:47], v[46:47], 1.0 op_sel_hi:[1,0]
	v_pk_mul_f32 v[42:43], v[42:43], s[52:53] op_sel_hi:[1,0]
	v_pk_mul_f32 v[40:41], v[40:41], s[52:53] op_sel_hi:[1,0]
	v_exp_f32_e32 v44, v44
	v_exp_f32_e32 v45, v45
	v_rcp_f32_e32 v46, v46
	v_rcp_f32_e32 v47, v47
	v_exp_f32_e32 v40, v40
	v_exp_f32_e32 v96, v42
	v_exp_f32_e32 v97, v43
	v_exp_f32_e32 v41, v41
	s_nop 0
	v_lshlrev_b32_e32 v114, 16, v148
	v_and_b32_e32 v115, 0xffff0000, v148
	v_lshlrev_b32_e32 v148, 16, v149
	v_and_b32_e32 v149, 0xffff0000, v149
	v_pk_fma_f32 v[100:101], v[86:87], v[100:101], v[90:91]
	v_pk_add_f32 v[44:45], v[44:45], 1.0 op_sel_hi:[1,0]
	v_pk_fma_f32 v[42:43], v[46:47], v[148:149], v[100:101]
	v_pk_add_f32 v[46:47], v[96:97], 1.0 op_sel_hi:[1,0]
	v_pk_add_f32 v[40:41], v[40:41], 1.0 op_sel_hi:[1,0]
	v_rcp_f32_e32 v44, v44
	v_rcp_f32_e32 v45, v45
	v_rcp_f32_e32 v46, v46
	v_rcp_f32_e32 v47, v47
	v_rcp_f32_e32 v96, v40
	v_rcp_f32_e32 v97, v41
	v_lshlrev_b32_e32 v120, 16, v150
	v_and_b32_e32 v121, 0xffff0000, v150
	v_lshlrev_b32_e32 v150, 16, v151
	v_and_b32_e32 v151, 0xffff0000, v151
	v_pk_fma_f32 v[98:99], v[84:85], v[98:99], v[88:89]
	v_pk_fma_f32 v[102:103], v[72:73], v[102:103], v[76:77]
	v_pk_fma_f32 v[112:113], v[74:75], v[112:113], v[78:79]
	v_pk_fma_f32 v[40:41], v[44:45], v[114:115], v[98:99]
	v_pk_fma_f32 v[46:47], v[46:47], v[150:151], v[112:113]
	s_and_b64 vcc, exec, s[4:5]
	v_pk_fma_f32 v[44:45], v[96:97], v[120:121], v[102:103]
	s_cbranch_vccnz .LBB0_1434
	v_lshl_add_u64 v[96:97], s[6:7], 0, v[218:219]
	global_store_dwordx4 v[96:97], v[40:43], off nt
	global_store_dwordx4 v[96:97], v[44:47], off offset:16 nt
	s_cbranch_execnz .LBB0_1406

.LBB0_1406:
	ds_read_b64 v[40:41], v205 offset:384
	s_nop 0
	v_lshlrev_b32_e32 v46, 16, v170
	v_and_b32_e32 v47, 0xffff0000, v170
	s_nop 0
	v_lshlrev_b32_e32 v98, 16, v172
	v_and_b32_e32 v99, 0xffff0000, v172
	s_waitcnt lgkmcnt(0)
	v_mul_f32_e64 v170, v41, -v40
	v_lshlrev_b32_e32 v100, 16, v173
	v_and_b32_e32 v101, 0xffff0000, v173
	v_pk_fma_f32 v[108:109], v[70:71], v[170:171], v[94:95] op_sel_hi:[1,0,1]
	v_lshlrev_b32_e32 v42, 16, v168
	v_pk_fma_f32 v[38:39], v[38:39], v[40:41], v[108:109] op_sel:[0,1,0]
	v_and_b32_e32 v43, 0xffff0000, v168
	v_pk_mul_f32 v[38:39], v[38:39], s[52:53] op_sel_hi:[1,0]
	v_lshlrev_b32_e32 v44, 16, v169
	v_exp_f32_e32 v38, v38
	v_exp_f32_e32 v39, v39
	v_and_b32_e32 v45, 0xffff0000, v169
	v_lshlrev_b32_e32 v96, 16, v171
	v_and_b32_e32 v97, 0xffff0000, v171
	v_lshlrev_b32_e32 v102, 16, v174
	v_and_b32_e32 v103, 0xffff0000, v174
	v_lshlrev_b32_e32 v104, 16, v175
	v_and_b32_e32 v105, 0xffff0000, v175
	v_pk_fma_f32 v[44:45], v[40:41], v[44:45], v[170:171] op_sel:[1,0,0] op_sel_hi:[1,1,0]
	v_pk_fma_f32 v[42:43], v[40:41], v[42:43], v[170:171] op_sel:[1,0,0] op_sel_hi:[1,1,0]
	v_pk_fma_f32 v[96:97], v[40:41], v[96:97], v[170:171] op_sel:[1,0,0] op_sel_hi:[1,1,0]
	v_pk_fma_f32 v[46:47], v[40:41], v[46:47], v[170:171] op_sel:[1,0,0] op_sel_hi:[1,1,0]
	v_pk_fma_f32 v[110:111], v[68:69], v[170:171], v[92:93] op_sel_hi:[1,0,1]
	v_pk_fma_f32 v[108:109], v[66:67], v[170:171], v[82:83] op_sel_hi:[1,0,1]
	v_pk_fma_f32 v[170:171], v[64:65], v[170:171], v[80:81] op_sel_hi:[1,0,1]
	v_pk_fma_f32 v[36:37], v[36:37], v[40:41], v[110:111] op_sel:[0,1,0]
	v_pk_fma_f32 v[34:35], v[34:35], v[40:41], v[108:109] op_sel:[0,1,0]
	v_pk_fma_f32 v[32:33], v[32:33], v[40:41], v[170:171] op_sel:[0,1,0]
	v_pk_mul_f32 v[36:37], v[36:37], s[52:53] op_sel_hi:[1,0]
	v_pk_add_f32 v[38:39], v[38:39], 1.0 op_sel_hi:[1,0]
	v_pk_mul_f32 v[34:35], v[34:35], s[52:53] op_sel_hi:[1,0]
	v_pk_mul_f32 v[32:33], v[32:33], s[52:53] op_sel_hi:[1,0]
	v_exp_f32_e32 v36, v36
	v_exp_f32_e32 v37, v37
	v_rcp_f32_e32 v38, v38
	v_rcp_f32_e32 v39, v39
	v_exp_f32_e32 v32, v32
	v_exp_f32_e32 v40, v34
	v_exp_f32_e32 v41, v35
	v_exp_f32_e32 v33, v33
	v_pk_fma_f32 v[44:45], v[86:87], v[44:45], v[90:91]
	v_pk_add_f32 v[36:37], v[36:37], 1.0 op_sel_hi:[1,0]
	v_pk_fma_f32 v[34:35], v[38:39], v[100:101], v[44:45]
	v_pk_add_f32 v[38:39], v[40:41], 1.0 op_sel_hi:[1,0]
	v_pk_add_f32 v[32:33], v[32:33], 1.0 op_sel_hi:[1,0]
	v_rcp_f32_e32 v36, v36
	v_rcp_f32_e32 v37, v37
	v_rcp_f32_e32 v38, v38
	v_rcp_f32_e32 v39, v39
	v_rcp_f32_e32 v40, v32
	v_rcp_f32_e32 v41, v33
	v_pk_fma_f32 v[42:43], v[84:85], v[42:43], v[88:89]
	v_pk_fma_f32 v[46:47], v[72:73], v[46:47], v[76:77]
	v_pk_fma_f32 v[96:97], v[74:75], v[96:97], v[78:79]
	v_pk_fma_f32 v[32:33], v[36:37], v[98:99], v[42:43]
	v_pk_fma_f32 v[38:39], v[38:39], v[104:105], v[96:97]
	s_and_b64 vcc, exec, s[4:5]
	v_pk_fma_f32 v[36:37], v[40:41], v[102:103], v[46:47]
	s_cbranch_vccnz .LBB0_1435
	v_lshl_add_u64 v[40:41], s[76:77], 0, v[218:219]
	global_store_dwordx4 v[40:41], v[32:35], off nt
	global_store_dwordx4 v[40:41], v[36:39], off offset:16 nt
	s_cbranch_execnz .LBB0_1409

.LBB0_1409:
	s_nop 1
	s_nop 0
	ds_read_b64 v[96:97], v205 offset:1024
	s_nop 0
	s_nop 0
	s_nop 0
	s_nop 0
	s_waitcnt lgkmcnt(0)
	v_mul_f32_e64 v170, v97, -v96
	s_nop 0
	s_nop 0
	s_nop 0
	v_pk_fma_f32 v[108:109], v[70:71], v[170:171], v[94:95] op_sel_hi:[1,0,1]
	s_nop 0
	s_nop 0
	s_nop 0
	s_nop 0
	s_nop 0
	s_nop 0
	s_nop 0
	v_pk_fma_f32 v[30:31], v[30:31], v[96:97], v[108:109] op_sel:[0,1,0]
	s_nop 0
	s_waitcnt vmcnt(8)
	v_lshlrev_b32_e32 v98, 16, v116
	v_pk_mul_f32 v[30:31], v[30:31], s[52:53] op_sel_hi:[1,0]
	v_and_b32_e32 v99, 0xffff0000, v116
	v_exp_f32_e32 v30, v30
	v_exp_f32_e32 v31, v31
	v_lshlrev_b32_e32 v116, 16, v117
	v_and_b32_e32 v117, 0xffff0000, v117
	v_lshlrev_b32_e32 v100, 16, v118
	v_and_b32_e32 v101, 0xffff0000, v118
	v_lshlrev_b32_e32 v118, 16, v119
	v_and_b32_e32 v119, 0xffff0000, v119
	v_pk_fma_f32 v[116:117], v[96:97], v[116:117], v[170:171] op_sel:[1,0,0] op_sel_hi:[1,1,0]
	v_pk_fma_f32 v[98:99], v[96:97], v[98:99], v[170:171] op_sel:[1,0,0] op_sel_hi:[1,1,0]
	v_pk_fma_f32 v[118:119], v[96:97], v[118:119], v[170:171] op_sel:[1,0,0] op_sel_hi:[1,1,0]
	v_pk_fma_f32 v[100:101], v[96:97], v[100:101], v[170:171] op_sel:[1,0,0] op_sel_hi:[1,1,0]
	v_pk_fma_f32 v[110:111], v[68:69], v[170:171], v[92:93] op_sel_hi:[1,0,1]
	v_pk_fma_f32 v[108:109], v[66:67], v[170:171], v[82:83] op_sel_hi:[1,0,1]
	v_pk_fma_f32 v[170:171], v[64:65], v[170:171], v[80:81] op_sel_hi:[1,0,1]
	v_pk_fma_f32 v[28:29], v[28:29], v[96:97], v[110:111] op_sel:[0,1,0]
	v_pk_fma_f32 v[26:27], v[26:27], v[96:97], v[108:109] op_sel:[0,1,0]
	v_pk_fma_f32 v[24:25], v[24:25], v[96:97], v[170:171] op_sel:[0,1,0]
	v_pk_mul_f32 v[28:29], v[28:29], s[52:53] op_sel_hi:[1,0]
	v_pk_add_f32 v[30:31], v[30:31], 1.0 op_sel_hi:[1,0]
	v_pk_mul_f32 v[26:27], v[26:27], s[52:53] op_sel_hi:[1,0]
	v_pk_mul_f32 v[24:25], v[24:25], s[52:53] op_sel_hi:[1,0]
	v_exp_f32_e32 v28, v28
	v_exp_f32_e32 v29, v29
	v_rcp_f32_e32 v30, v30
	v_rcp_f32_e32 v31, v31
	v_exp_f32_e32 v24, v24
	v_exp_f32_e32 v96, v26
	v_exp_f32_e32 v97, v27
	v_exp_f32_e32 v25, v25
	s_nop 0
	v_lshlrev_b32_e32 v102, 16, v152
	v_and_b32_e32 v103, 0xffff0000, v152
	v_lshlrev_b32_e32 v152, 16, v153
	v_and_b32_e32 v153, 0xffff0000, v153
	v_pk_fma_f32 v[116:117], v[86:87], v[116:117], v[90:91]
	v_pk_add_f32 v[28:29], v[28:29], 1.0 op_sel_hi:[1,0]
	v_pk_fma_f32 v[26:27], v[30:31], v[152:153], v[116:117]
	v_pk_add_f32 v[30:31], v[96:97], 1.0 op_sel_hi:[1,0]
	v_pk_add_f32 v[24:25], v[24:25], 1.0 op_sel_hi:[1,0]
	v_rcp_f32_e32 v28, v28
	v_rcp_f32_e32 v29, v29
	v_rcp_f32_e32 v30, v30
	v_rcp_f32_e32 v31, v31
	v_rcp_f32_e32 v56, v24
	v_rcp_f32_e32 v57, v25
	v_lshlrev_b32_e32 v104, 16, v154
	v_and_b32_e32 v105, 0xffff0000, v154
	v_lshlrev_b32_e32 v154, 16, v155
	v_and_b32_e32 v155, 0xffff0000, v155
	v_pk_fma_f32 v[98:99], v[84:85], v[98:99], v[88:89]
	v_pk_fma_f32 v[100:101], v[72:73], v[100:101], v[76:77]
	v_pk_fma_f32 v[118:119], v[74:75], v[118:119], v[78:79]
	v_pk_fma_f32 v[24:25], v[28:29], v[102:103], v[98:99]
	v_pk_fma_f32 v[30:31], v[30:31], v[154:155], v[118:119]
	s_and_b64 vcc, exec, s[4:5]
	v_pk_fma_f32 v[28:29], v[56:57], v[104:105], v[100:101]
	s_cbranch_vccnz .LBB0_1436
	v_lshl_add_u64 v[56:57], s[18:19], 0, v[218:219]
	global_store_dwordx4 v[56:57], v[24:27], off nt
	global_store_dwordx4 v[56:57], v[28:31], off offset:16 nt
	s_cbranch_execnz .LBB0_1412

.LBB0_1412:
	ds_read_b64 v[24:25], v205 offset:1152
	s_nop 0
	v_lshlrev_b32_e32 v26, 16, v156
	v_and_b32_e32 v27, 0xffff0000, v156
	v_lshlrev_b32_e32 v28, 16, v157
	v_and_b32_e32 v29, 0xffff0000, v157
	s_waitcnt lgkmcnt(0)
	v_mul_f32_e64 v118, v25, -v24
	v_pk_fma_f32 v[60:61], v[70:71], v[118:119], v[94:95] op_sel_hi:[1,0,1]
	v_lshlrev_b32_e32 v30, 16, v158
	v_pk_fma_f32 v[22:23], v[22:23], v[24:25], v[60:61] op_sel:[0,1,0]
	v_and_b32_e32 v31, 0xffff0000, v158
	v_pk_mul_f32 v[22:23], v[22:23], s[52:53] op_sel_hi:[1,0]
	v_lshlrev_b32_e32 v48, 16, v159
	v_exp_f32_e32 v22, v22
	v_exp_f32_e32 v23, v23
	v_and_b32_e32 v49, 0xffff0000, v159
	v_pk_fma_f32 v[28:29], v[24:25], v[28:29], v[118:119] op_sel:[1,0,0] op_sel_hi:[1,1,0]
	v_pk_fma_f32 v[26:27], v[24:25], v[26:27], v[118:119] op_sel:[1,0,0] op_sel_hi:[1,1,0]
	v_pk_fma_f32 v[48:49], v[24:25], v[48:49], v[118:119] op_sel:[1,0,0] op_sel_hi:[1,1,0]
	v_pk_fma_f32 v[30:31], v[24:25], v[30:31], v[118:119] op_sel:[1,0,0] op_sel_hi:[1,1,0]
	v_pk_fma_f32 v[62:63], v[68:69], v[118:119], v[92:93] op_sel_hi:[1,0,1]
	v_pk_fma_f32 v[60:61], v[66:67], v[118:119], v[82:83] op_sel_hi:[1,0,1]
	v_pk_fma_f32 v[118:119], v[64:65], v[118:119], v[80:81] op_sel_hi:[1,0,1]
	v_pk_fma_f32 v[20:21], v[20:21], v[24:25], v[62:63] op_sel:[0,1,0]
	v_pk_fma_f32 v[18:19], v[18:19], v[24:25], v[60:61] op_sel:[0,1,0]
	v_pk_fma_f32 v[16:17], v[16:17], v[24:25], v[118:119] op_sel:[0,1,0]
	v_pk_mul_f32 v[20:21], v[20:21], s[52:53] op_sel_hi:[1,0]
	v_pk_add_f32 v[22:23], v[22:23], 1.0 op_sel_hi:[1,0]
	v_pk_mul_f32 v[18:19], v[18:19], s[52:53] op_sel_hi:[1,0]
	v_pk_mul_f32 v[16:17], v[16:17], s[52:53] op_sel_hi:[1,0]
	v_exp_f32_e32 v20, v20
	v_exp_f32_e32 v21, v21
	v_rcp_f32_e32 v22, v22
	v_rcp_f32_e32 v23, v23
	v_exp_f32_e32 v16, v16
	v_exp_f32_e32 v24, v18
	v_exp_f32_e32 v25, v19
	v_exp_f32_e32 v17, v17
	s_nop 0
	v_lshlrev_b32_e32 v50, 16, v160
	v_and_b32_e32 v51, 0xffff0000, v160
	v_lshlrev_b32_e32 v160, 16, v161
	v_and_b32_e32 v161, 0xffff0000, v161
	v_pk_fma_f32 v[28:29], v[86:87], v[28:29], v[90:91]
	v_pk_add_f32 v[20:21], v[20:21], 1.0 op_sel_hi:[1,0]
	v_pk_fma_f32 v[18:19], v[22:23], v[160:161], v[28:29]
	v_pk_add_f32 v[22:23], v[24:25], 1.0 op_sel_hi:[1,0]
	v_pk_add_f32 v[16:17], v[16:17], 1.0 op_sel_hi:[1,0]
	v_rcp_f32_e32 v20, v20
	v_rcp_f32_e32 v21, v21
	v_rcp_f32_e32 v22, v22
	v_rcp_f32_e32 v23, v23
	v_rcp_f32_e32 v24, v16
	v_rcp_f32_e32 v25, v17
	v_lshlrev_b32_e32 v56, 16, v162
	v_and_b32_e32 v57, 0xffff0000, v162
	v_lshlrev_b32_e32 v162, 16, v163
	v_and_b32_e32 v163, 0xffff0000, v163
	v_pk_fma_f32 v[26:27], v[84:85], v[26:27], v[88:89]
	v_pk_fma_f32 v[30:31], v[72:73], v[30:31], v[76:77]
	v_pk_fma_f32 v[48:49], v[74:75], v[48:49], v[78:79]
	v_pk_fma_f32 v[16:17], v[20:21], v[50:51], v[26:27]
	v_pk_fma_f32 v[22:23], v[22:23], v[162:163], v[48:49]
	s_and_b64 vcc, exec, s[4:5]
	v_pk_fma_f32 v[20:21], v[24:25], v[56:57], v[30:31]
	s_cbranch_vccnz .LBB0_1437
	v_lshl_add_u64 v[24:25], s[14:15], 0, v[218:219]
	global_store_dwordx4 v[24:25], v[16:19], off nt
	global_store_dwordx4 v[24:25], v[20:23], off offset:16 nt
	s_cbranch_execnz .LBB0_1415

.LBB0_1415:
	ds_read_b64 v[16:17], v205 offset:1280
	s_nop 0
	s_waitcnt vmcnt(4)
	v_lshlrev_b32_e32 v22, 16, v54
	v_and_b32_e32 v23, 0xffff0000, v54
	s_nop 0
	v_lshlrev_b32_e32 v26, 16, v128
	v_and_b32_e32 v27, 0xffff0000, v128
	s_waitcnt lgkmcnt(0)
	v_mul_f32_e64 v54, v17, -v16
	v_lshlrev_b32_e32 v28, 16, v129
	v_and_b32_e32 v29, 0xffff0000, v129
	v_pk_fma_f32 v[44:45], v[70:71], v[54:55], v[94:95] op_sel_hi:[1,0,1]
	v_lshlrev_b32_e32 v18, 16, v52
	v_pk_fma_f32 v[14:15], v[14:15], v[16:17], v[44:45] op_sel:[0,1,0]
	v_and_b32_e32 v19, 0xffff0000, v52
	v_pk_mul_f32 v[14:15], v[14:15], s[52:53] op_sel_hi:[1,0]
	v_lshlrev_b32_e32 v20, 16, v53
	v_exp_f32_e32 v14, v14
	v_exp_f32_e32 v15, v15
	v_and_b32_e32 v21, 0xffff0000, v53
	v_lshlrev_b32_e32 v24, 16, v55
	v_and_b32_e32 v25, 0xffff0000, v55
	v_lshlrev_b32_e32 v30, 16, v130
	v_and_b32_e32 v31, 0xffff0000, v130
	v_lshlrev_b32_e32 v40, 16, v131
	v_and_b32_e32 v41, 0xffff0000, v131
	v_pk_fma_f32 v[20:21], v[16:17], v[20:21], v[54:55] op_sel:[1,0,0] op_sel_hi:[1,1,0]
	v_pk_fma_f32 v[18:19], v[16:17], v[18:19], v[54:55] op_sel:[1,0,0] op_sel_hi:[1,1,0]
	v_pk_fma_f32 v[24:25], v[16:17], v[24:25], v[54:55] op_sel:[1,0,0] op_sel_hi:[1,1,0]
	v_pk_fma_f32 v[22:23], v[16:17], v[22:23], v[54:55] op_sel:[1,0,0] op_sel_hi:[1,1,0]
	v_pk_fma_f32 v[46:47], v[68:69], v[54:55], v[92:93] op_sel_hi:[1,0,1]
	v_pk_fma_f32 v[44:45], v[66:67], v[54:55], v[82:83] op_sel_hi:[1,0,1]
	v_pk_fma_f32 v[54:55], v[64:65], v[54:55], v[80:81] op_sel_hi:[1,0,1]
	v_pk_fma_f32 v[12:13], v[12:13], v[16:17], v[46:47] op_sel:[0,1,0]
	v_pk_fma_f32 v[10:11], v[10:11], v[16:17], v[44:45] op_sel:[0,1,0]
	v_pk_fma_f32 v[8:9], v[8:9], v[16:17], v[54:55] op_sel:[0,1,0]
	v_pk_mul_f32 v[12:13], v[12:13], s[52:53] op_sel_hi:[1,0]
	v_pk_add_f32 v[14:15], v[14:15], 1.0 op_sel_hi:[1,0]
	v_pk_mul_f32 v[10:11], v[10:11], s[52:53] op_sel_hi:[1,0]
	v_pk_mul_f32 v[8:9], v[8:9], s[52:53] op_sel_hi:[1,0]
	v_exp_f32_e32 v12, v12
	v_exp_f32_e32 v13, v13
	v_rcp_f32_e32 v14, v14
	v_rcp_f32_e32 v15, v15
	v_exp_f32_e32 v8, v8
	v_exp_f32_e32 v16, v10
	v_exp_f32_e32 v17, v11
	v_exp_f32_e32 v9, v9
	v_pk_fma_f32 v[20:21], v[86:87], v[20:21], v[90:91]
	v_pk_add_f32 v[12:13], v[12:13], 1.0 op_sel_hi:[1,0]
	v_pk_fma_f32 v[10:11], v[14:15], v[28:29], v[20:21]
	v_pk_add_f32 v[14:15], v[16:17], 1.0 op_sel_hi:[1,0]
	v_pk_add_f32 v[8:9], v[8:9], 1.0 op_sel_hi:[1,0]
	v_rcp_f32_e32 v12, v12
	v_rcp_f32_e32 v13, v13
	v_rcp_f32_e32 v14, v14
	v_rcp_f32_e32 v15, v15
	v_rcp_f32_e32 v16, v8
	v_rcp_f32_e32 v17, v9
	v_pk_fma_f32 v[18:19], v[84:85], v[18:19], v[88:89]
	v_pk_fma_f32 v[22:23], v[72:73], v[22:23], v[76:77]
	v_pk_fma_f32 v[24:25], v[74:75], v[24:25], v[78:79]
	v_pk_fma_f32 v[8:9], v[12:13], v[26:27], v[18:19]
	v_pk_fma_f32 v[14:15], v[14:15], v[40:41], v[24:25]
	s_and_b64 vcc, exec, s[4:5]
	v_pk_fma_f32 v[12:13], v[16:17], v[30:31], v[22:23]
	s_cbranch_vccnz .LBB0_1438
	v_lshl_add_u64 v[16:17], s[58:59], 0, v[218:219]
	global_store_dwordx4 v[16:17], v[8:11], off nt
	global_store_dwordx4 v[16:17], v[12:15], off offset:16 nt
	s_cbranch_execnz .LBB0_1418

.LBB0_1418:
	ds_read_b64 v[8:9], v205 offset:1408
	s_nop 0
	v_lshlrev_b32_e32 v10, 16, v132
	v_and_b32_e32 v11, 0xffff0000, v132
	v_lshlrev_b32_e32 v12, 16, v133
	v_and_b32_e32 v13, 0xffff0000, v133
	s_waitcnt lgkmcnt(0)
	v_mul_f32_e64 v26, v9, -v8
	v_pk_fma_f32 v[28:29], v[70:71], v[26:27], v[94:95] op_sel_hi:[1,0,1]
	v_lshlrev_b32_e32 v14, 16, v134
	v_pk_fma_f32 v[6:7], v[6:7], v[8:9], v[28:29] op_sel:[0,1,0]
	v_and_b32_e32 v15, 0xffff0000, v134
	v_pk_mul_f32 v[6:7], v[6:7], s[52:53] op_sel_hi:[1,0]
	v_lshlrev_b32_e32 v16, 16, v135
	v_exp_f32_e32 v6, v6
	v_exp_f32_e32 v7, v7
	v_and_b32_e32 v17, 0xffff0000, v135
	v_pk_fma_f32 v[12:13], v[8:9], v[12:13], v[26:27] op_sel:[1,0,0] op_sel_hi:[1,1,0]
	v_pk_fma_f32 v[10:11], v[8:9], v[10:11], v[26:27] op_sel:[1,0,0] op_sel_hi:[1,1,0]
	v_pk_fma_f32 v[16:17], v[8:9], v[16:17], v[26:27] op_sel:[1,0,0] op_sel_hi:[1,1,0]
	v_pk_fma_f32 v[14:15], v[8:9], v[14:15], v[26:27] op_sel:[1,0,0] op_sel_hi:[1,1,0]
	v_pk_fma_f32 v[30:31], v[68:69], v[26:27], v[92:93] op_sel_hi:[1,0,1]
	v_pk_fma_f32 v[28:29], v[66:67], v[26:27], v[82:83] op_sel_hi:[1,0,1]
	v_pk_fma_f32 v[26:27], v[64:65], v[26:27], v[80:81] op_sel_hi:[1,0,1]
	v_pk_fma_f32 v[4:5], v[4:5], v[8:9], v[30:31] op_sel:[0,1,0]
	v_pk_fma_f32 v[2:3], v[2:3], v[8:9], v[28:29] op_sel:[0,1,0]
	v_pk_fma_f32 v[0:1], v[0:1], v[8:9], v[26:27] op_sel:[0,1,0]
	v_pk_mul_f32 v[4:5], v[4:5], s[52:53] op_sel_hi:[1,0]
	v_pk_add_f32 v[6:7], v[6:7], 1.0 op_sel_hi:[1,0]
	v_pk_mul_f32 v[2:3], v[2:3], s[52:53] op_sel_hi:[1,0]
	v_pk_mul_f32 v[0:1], v[0:1], s[52:53] op_sel_hi:[1,0]
	v_exp_f32_e32 v4, v4
	v_exp_f32_e32 v5, v5
	v_rcp_f32_e32 v6, v6
	v_rcp_f32_e32 v7, v7
	v_exp_f32_e32 v0, v0
	v_exp_f32_e32 v8, v2
	v_exp_f32_e32 v9, v3
	v_exp_f32_e32 v1, v1
	s_nop 0
	v_lshlrev_b32_e32 v20, 16, v137
	v_and_b32_e32 v21, 0xffff0000, v137
	v_pk_fma_f32 v[12:13], v[86:87], v[12:13], v[90:91]
	v_pk_add_f32 v[4:5], v[4:5], 1.0 op_sel_hi:[1,0]
	v_pk_fma_f32 v[2:3], v[6:7], v[20:21], v[12:13]
	v_pk_add_f32 v[6:7], v[8:9], 1.0 op_sel_hi:[1,0]
	v_pk_add_f32 v[0:1], v[0:1], 1.0 op_sel_hi:[1,0]
	v_rcp_f32_e32 v4, v4
	v_rcp_f32_e32 v5, v5
	v_rcp_f32_e32 v6, v6
	v_rcp_f32_e32 v7, v7
	v_rcp_f32_e32 v8, v0
	v_rcp_f32_e32 v9, v1
	v_lshlrev_b32_e32 v18, 16, v136
	v_and_b32_e32 v19, 0xffff0000, v136
	v_lshlrev_b32_e32 v22, 16, v138
	v_and_b32_e32 v23, 0xffff0000, v138
	v_lshlrev_b32_e32 v24, 16, v139
	v_and_b32_e32 v25, 0xffff0000, v139
	v_pk_fma_f32 v[10:11], v[84:85], v[10:11], v[88:89]
	v_pk_fma_f32 v[14:15], v[72:73], v[14:15], v[76:77]
	v_pk_fma_f32 v[16:17], v[74:75], v[16:17], v[78:79]
	v_pk_fma_f32 v[0:1], v[4:5], v[18:19], v[10:11]
	v_pk_fma_f32 v[6:7], v[6:7], v[24:25], v[16:17]
	s_and_b64 vcc, exec, s[4:5]
	v_pk_fma_f32 v[4:5], v[8:9], v[22:23], v[14:15]
	s_cbranch_vccnz .LBB0_1439
	v_lshl_add_u64 v[8:9], s[62:63], 0, v[218:219]
	global_store_dwordx4 v[8:9], v[0:3], off nt
	global_store_dwordx4 v[8:9], v[4:7], off offset:16 nt
	s_cbranch_execnz .LBB0_1421
